# speedup vs baseline: 1.0191x; 1.0046x over previous
; __device__ __forceinline__ int unit_jlo_fref(int head, int P0, const Bases& bs, const float* nrm, double& fref) {
;     const int lane = (int)__builtin_amdgcn_mbcnt_hi(~0u, __builtin_amdgcn_mbcnt_lo(~0u, 0u));
;     const double* Fh = bs.F + (size_t)head * SEQ; const float* nq = nrm + head * 4; const float* nk = nrm + 32 + head * 4;
;     const int nj = P0 / KVBLK;
;     const float q0 = nq[0], q1 = nq[1], q2 = nq[2], q3 = nq[3], k0 = nk[0], k1 = nk[1], k2 = nk[2], k3 = nk[3];
;     const double fp = Fh[P0];
;     double fv[4];
; #pragma unroll
;     for (int q = 0; q < 4; ++q) { const int j = lane + 64 * q; fv[q] = Fh[KVBLK * (j < nj ? j : 0) + KVBLK - 1]; }
;     const float B = 2.f * sqrtf(((q0 + q1) + (q2 + q3)) * ((k0 + k1) + (k2 + k3))) * SCALE + 105.f;
;     const double nb = -(double)B; int cnt = 0;
; #pragma unroll
;     for (int q = 0; q < 4; ++q) { const int j = lane + 64 * q; const bool pr = (j < nj) && ((fp - fv[q]) < nb); cnt += __builtin_popcountll(__ballot(pr)); }
;     const unsigned long long b = __builtin_bit_cast(unsigned long long, fp);
;     const unsigned lo = __builtin_amdgcn_readfirstlane((unsigned)b), hi = __builtin_amdgcn_readfirstlane((unsigned)(b >> 32));
;     fref = __builtin_bit_cast(double, ((unsigned long long)hi << 32) | lo);
;     return __builtin_amdgcn_readfirstlane(cnt);
; }
; __device__ __forceinline__ bool decode_item(int head, int e, const Bases& bs, const float* nrm, Item& it) {
;     int k, qb;
;     if (e < 64) { k = 0; qb = 63 - e; } else if (e < 112) { k = 1; qb = 63 - (e - 64); } else if (e < 144) { k = 2; qb = 63 - (e - 112); } else { k = 3; qb = 63 - (e - 144); }
;     it.head = head; it.P0 = qb * QB;
;     const int jl = unit_jlo_fref(head, it.P0, bs, nrm, it.fref), ntf = it.P0 / KVBLK + QB / KVBLK, kf = jl / SEGT, kl = qb >> 4;
;     if (k < kf) return false;
;     const int s0 = jl > k * SEGT ? jl : k * SEGT, s1 = (k + 1) * SEGT < ntf ? (k + 1) * SEGT : ntf;
;     it.jlo = s0; it.nt = s1 - s0; it.part = kf == kl ? -1 : slot_base(head, qb) + k;
;     return true;
; }
.LBB0_183:
	s_or_b64 exec, exec, s[2:3]
	v_mov_b32_e32 v0, s73
	s_waitcnt lgkmcnt(0)
	s_barrier
	ds_read_b32 v0, v0
	s_waitcnt lgkmcnt(0)
	s_barrier
	v_readfirstlane_b32 s2, v0
	s_cmpk_lt_i32 s2, 0xa0
	s_cbranch_scc0 .LBB0_185
	s_sub_i32 s3, s2, 0x64
	s_and_b32 s8, s3, 3
	s_ashr_i32 s3, s3, 2
	s_lshl_b32 s19, s8, 4
	s_sub_i32 s19, s19, s3
	s_add_i32 s19, s19, 14
	s_mov_b32 s18, s8
	s_sub_i32 s3, 0xa2, s2
	s_cmp_lt_i32 s2, 0x64
	s_cselect_b32 s19, s3, s19
	s_cselect_b32 s18, 3, s18
	s_sub_i32 s3, 0x91, s2
	s_cmp_lt_i32 s2, 0x63
	s_cselect_b32 s19, s3, s19
	s_cselect_b32 s18, 2, s18
	s_sub_i32 s3, 0x70, s2
	s_cmp_lt_i32 s2, 0x52
	s_cselect_b32 s19, s3, s19
	s_cselect_b32 s18, 1, s18
	s_sub_i32 s3, 63, s2
	s_cmp_lt_i32 s2, 49
	s_cselect_b32 s19, s3, s19
	s_cselect_b32 s18, 0, s18
	s_lshl_b32 s86, s19, 8
	s_lshl_b32 s2, s76, 17
	v_readlane_b32 s3, v255, 34
	s_add_u32 s2, s3, s2
	s_addc_u32 s3, s81, 0
	s_lshr_b32 s15, s86, 6
	s_lshl_b32 s14, s76, 4
	s_lshl_b64 s[8:9], s[86:87], 3
	v_cmp_gt_i32_e64 s[12:13], s15, v200
	v_lshl_or_b32 v2, v200, 6, 63
	s_add_u32 s8, s2, s8
	v_cndmask_b32_e64 v2, 63, v2, s[12:13]
	s_addc_u32 s9, s3, s9
	v_lshlrev_b32_e32 v2, 3, v2
	global_load_dwordx2 v[0:1], v181, s[8:9]
	global_load_dwordx2 v[14:15], v2, s[2:3]
	v_add_u32_e32 v2, 64, v200
	v_cmp_gt_i32_e64 s[10:11], s15, v2
	v_lshl_or_b32 v2, v2, 6, 63
	v_mov_b32_e32 v10, s14
	v_cndmask_b32_e64 v2, 63, v2, s[10:11]
	v_lshlrev_b32_e32 v2, 3, v2
	global_load_dwordx2 v[16:17], v2, s[2:3]
	v_or_b32_e32 v2, 0x80, v200
	v_cmp_gt_i32_e64 s[8:9], s15, v2
	v_lshl_or_b32 v2, v2, 6, 63
	s_waitcnt vmcnt(0)
	v_readfirstlane_b32 s95, v1
	v_cndmask_b32_e64 v2, 63, v2, s[8:9]
	v_lshlrev_b32_e32 v2, 3, v2
	global_load_dwordx2 v[4:5], v2, s[2:3]
	v_add_u32_e32 v2, 0xc0, v200
	v_cmp_gt_i32_e32 vcc, s15, v2
	v_lshl_or_b32 v2, v2, 6, 63
	v_readfirstlane_b32 s94, v0
	v_cndmask_b32_e32 v2, 63, v2, vcc
	v_lshlrev_b32_e32 v2, 3, v2
	global_load_dwordx2 v[2:3], v2, s[2:3]
	s_nop 0
	global_load_dwordx4 v[6:9], v10, s[4:5]
	s_nop 0
	global_load_dwordx4 v[10:13], v10, s[4:5] offset:128
	s_waitcnt vmcnt(3)
	v_add_f64 v[4:5], v[0:1], -v[4:5]
	s_waitcnt vmcnt(1)
	v_mov_b32_e32 v18, v6
	s_waitcnt vmcnt(0)
	v_mov_b32_e32 v19, v10
	v_mov_b32_e32 v10, v7
	v_pk_add_f32 v[6:7], v[18:19], v[10:11]
	v_mov_b32_e32 v10, v8
	v_mov_b32_e32 v11, v12
	v_mov_b32_e32 v12, v9
	v_pk_add_f32 v[8:9], v[10:11], v[12:13]
	v_add_f64 v[2:3], v[0:1], -v[2:3]
	v_pk_add_f32 v[6:7], v[6:7], v[8:9]
	s_nop 0
	v_mul_f32_e32 v6, v6, v7
	v_cmp_gt_f32_e64 s[14:15], s42, v6
	v_mul_f32_e32 v7, 0x4f800000, v6
	s_nop 0
	v_cndmask_b32_e64 v6, v6, v7, s[14:15]
	v_sqrt_f32_e32 v7, v6
	s_nop 0
	v_add_u32_e32 v8, -1, v7
	v_fma_f32 v9, -v8, v7, v6
	v_cmp_ge_f32_e64 s[16:17], 0, v9
	v_add_u32_e32 v9, 1, v7
	s_nop 0
	v_cndmask_b32_e64 v8, v7, v8, s[16:17]
	v_fma_f32 v7, -v9, v7, v6
	v_cmp_lt_f32_e64 s[16:17], 0, v7
	s_nop 1
	v_cndmask_b32_e64 v7, v8, v9, s[16:17]
	v_mul_f32_e32 v8, 0x37800000, v7
	v_cndmask_b32_e64 v7, v7, v8, s[14:15]
	v_cmp_class_f32_e64 s[14:15], v6, v194
	v_add_f64 v[8:9], v[0:1], -v[14:15]
	s_nop 0
	v_cndmask_b32_e64 v6, v7, v6, s[14:15]
	v_add_f32_e32 v6, v6, v6
	v_fmamk_f32 v6, v6, 0x3db504f3, v195
	v_cvt_f64_f32_e32 v[6:7], v6
	v_cmp_lt_f64_e64 s[2:3], v[8:9], -v[6:7]
	s_and_b64 s[2:3], s[12:13], s[2:3]
	s_nop 0
	v_cndmask_b32_e64 v8, 0, 1, s[2:3]
	v_cmp_ne_u32_e64 s[12:13], 0, v8
	v_add_f64 v[8:9], v[0:1], -v[16:17]
	v_cmp_lt_f64_e64 s[2:3], v[8:9], -v[6:7]
	s_and_b64 s[2:3], s[10:11], s[2:3]
	s_bcnt1_i32_b64 s12, s[12:13]
	v_cndmask_b32_e64 v8, 0, 1, s[2:3]
	v_cmp_ne_u32_e64 s[10:11], 0, v8
	s_bcnt1_i32_b64 s2, s[10:11]
	s_add_i32 s10, s2, s12
	v_cmp_lt_f64_e64 s[2:3], v[4:5], -v[6:7]
	s_and_b64 s[2:3], s[8:9], s[2:3]
	s_nop 0
	v_cndmask_b32_e64 v4, 0, 1, s[2:3]
	v_cmp_ne_u32_e64 s[8:9], 0, v4
	s_bcnt1_i32_b64 s2, s[8:9]
	s_add_i32 s8, s10, s2
	v_cmp_lt_f64_e64 s[2:3], v[2:3], -v[6:7]
	s_and_b64 s[2:3], vcc, s[2:3]
	s_nop 0
	v_cndmask_b32_e64 v2, 0, 1, s[2:3]
	v_cmp_ne_u32_e32 vcc, 0, v2
	s_bcnt1_i32_b64 s2, vcc
	s_add_i32 s10, s8, s2
	s_ashr_i32 s2, s10, 31
	s_lshr_b32 s2, s2, 26
	s_add_i32 s2, s10, s2
	s_ashr_i32 s12, s2, 6
	s_cmp_lt_i32 s18, s12
	s_mov_b64 s[2:3], 0
	s_cselect_b64 s[8:9], -1, 0
	s_branch .LBB0_186

; __device__ __forceinline__ int unit_jlo_fref(int head, int P0, const Bases& bs, const float* nrm, double& fref) {
;     const int lane = (int)__builtin_amdgcn_mbcnt_hi(~0u, __builtin_amdgcn_mbcnt_lo(~0u, 0u));
;     const double* Fh = bs.F + (size_t)head * SEQ; const float* nq = nrm + head * 4; const float* nk = nrm + 32 + head * 4;
;     const int nj = P0 / KVBLK;
;     const float q0 = nq[0], q1 = nq[1], q2 = nq[2], q3 = nq[3], k0 = nk[0], k1 = nk[1], k2 = nk[2], k3 = nk[3];
;     const double fp = Fh[P0];
;     double fv[4];
; #pragma unroll
;     for (int q = 0; q < 4; ++q) { const int j = lane + 64 * q; fv[q] = Fh[KVBLK * (j < nj ? j : 0) + KVBLK - 1]; }
;     const float B = 2.f * sqrtf(((q0 + q1) + (q2 + q3)) * ((k0 + k1) + (k2 + k3))) * SCALE + 105.f;
;     const double nb = -(double)B; int cnt = 0;
; #pragma unroll
;     for (int q = 0; q < 4; ++q) { const int j = lane + 64 * q; const bool pr = (j < nj) && ((fp - fv[q]) < nb); cnt += __builtin_popcountll(__ballot(pr)); }
;     const unsigned long long b = __builtin_bit_cast(unsigned long long, fp);
;     const unsigned lo = __builtin_amdgcn_readfirstlane((unsigned)b), hi = __builtin_amdgcn_readfirstlane((unsigned)(b >> 32));
;     fref = __builtin_bit_cast(double, ((unsigned long long)hi << 32) | lo);
;     return __builtin_amdgcn_readfirstlane(cnt);
; }
; __device__ __forceinline__ bool decode_item(int head, int e, const Bases& bs, const float* nrm, Item& it) {
;     int k, qb;
;     if (e < 64) { k = 0; qb = 63 - e; } else if (e < 112) { k = 1; qb = 63 - (e - 64); } else if (e < 144) { k = 2; qb = 63 - (e - 112); } else { k = 3; qb = 63 - (e - 144); }
;     it.head = head; it.P0 = qb * QB;
;     const int jl = unit_jlo_fref(head, it.P0, bs, nrm, it.fref), ntf = it.P0 / KVBLK + QB / KVBLK, kf = jl / SEGT, kl = qb >> 4;
;     if (k < kf) return false;
;     const int s0 = jl > k * SEGT ? jl : k * SEGT, s1 = (k + 1) * SEGT < ntf ? (k + 1) * SEGT : ntf;
;     it.jlo = s0; it.nt = s1 - s0; it.part = kf == kl ? -1 : slot_base(head, qb) + k;
;     return true;
; }
.LBB0_212:
	s_or_b64 exec, exec, s[2:3]
	v_mov_b32_e32 v0, s73
	s_waitcnt lgkmcnt(0)
	s_barrier
	ds_read_b32 v0, v0
	s_waitcnt lgkmcnt(0)
	s_barrier
	v_readfirstlane_b32 s2, v0
	s_cmpk_lt_i32 s2, 0xa0
	s_cbranch_scc0 .LBB0_214
	s_sub_i32 s3, s2, 0x64
	s_and_b32 s8, s3, 3
	s_ashr_i32 s3, s3, 2
	s_lshl_b32 s21, s8, 4
	s_sub_i32 s21, s21, s3
	s_add_i32 s21, s21, 14
	s_mov_b32 s20, s8
	s_sub_i32 s3, 0xa2, s2
	s_cmp_lt_i32 s2, 0x64
	s_cselect_b32 s21, s3, s21
	s_cselect_b32 s20, 3, s20
	s_sub_i32 s3, 0x91, s2
	s_cmp_lt_i32 s2, 0x63
	s_cselect_b32 s21, s3, s21
	s_cselect_b32 s20, 2, s20
	s_sub_i32 s3, 0x70, s2
	s_cmp_lt_i32 s2, 0x52
	s_cselect_b32 s21, s3, s21
	s_cselect_b32 s20, 1, s20
	s_sub_i32 s3, 63, s2
	s_cmp_lt_i32 s2, 49
	s_cselect_b32 s21, s3, s21
	s_cselect_b32 s20, 0, s20
	s_lshl_b32 s86, s21, 8
	s_lshl_b32 s2, s19, 17
	v_readlane_b32 s3, v255, 34
	s_add_u32 s2, s3, s2
	s_addc_u32 s3, s81, 0
	s_lshr_b32 s15, s86, 6
	s_lshl_b32 s14, s19, 4
	s_lshl_b64 s[8:9], s[86:87], 3
	v_cmp_gt_i32_e64 s[12:13], s15, v200
	v_lshl_or_b32 v2, v200, 6, 63
	s_add_u32 s8, s2, s8
	v_cndmask_b32_e64 v2, 63, v2, s[12:13]
	s_addc_u32 s9, s3, s9
	v_lshlrev_b32_e32 v2, 3, v2
	global_load_dwordx2 v[0:1], v181, s[8:9]
	global_load_dwordx2 v[14:15], v2, s[2:3]
	v_add_u32_e32 v2, 64, v200
	v_cmp_gt_i32_e64 s[10:11], s15, v2
	v_lshl_or_b32 v2, v2, 6, 63
	v_mov_b32_e32 v10, s14
	v_cndmask_b32_e64 v2, 63, v2, s[10:11]
	v_lshlrev_b32_e32 v2, 3, v2
	global_load_dwordx2 v[16:17], v2, s[2:3]
	v_or_b32_e32 v2, 0x80, v200
	v_cmp_gt_i32_e64 s[8:9], s15, v2
	v_lshl_or_b32 v2, v2, 6, 63
	s_nop 0
	v_cndmask_b32_e64 v2, 63, v2, s[8:9]
	v_lshlrev_b32_e32 v2, 3, v2
	global_load_dwordx2 v[4:5], v2, s[2:3]
	v_add_u32_e32 v2, 0xc0, v200
	v_cmp_gt_i32_e32 vcc, s15, v2
	v_lshl_or_b32 v2, v2, 6, 63
	s_waitcnt vmcnt(0)
	v_add_f64 v[4:5], v[0:1], -v[4:5]
	v_cndmask_b32_e32 v2, 63, v2, vcc
	v_lshlrev_b32_e32 v2, 3, v2
	global_load_dwordx2 v[2:3], v2, s[2:3]
	s_nop 0
	global_load_dwordx4 v[6:9], v10, s[4:5]
	s_nop 0
	global_load_dwordx4 v[10:13], v10, s[4:5] offset:128
	s_waitcnt vmcnt(1)
	v_mov_b32_e32 v18, v6
	s_waitcnt vmcnt(0)
	v_mov_b32_e32 v19, v10
	v_mov_b32_e32 v10, v7
	v_pk_add_f32 v[6:7], v[18:19], v[10:11]
	v_mov_b32_e32 v10, v8
	v_mov_b32_e32 v11, v12
	v_mov_b32_e32 v12, v9
	v_pk_add_f32 v[8:9], v[10:11], v[12:13]
	v_add_f64 v[2:3], v[0:1], -v[2:3]
	v_pk_add_f32 v[6:7], v[6:7], v[8:9]
	s_nop 0
	v_mul_f32_e32 v6, v6, v7
	v_cmp_gt_f32_e64 s[14:15], s42, v6
	v_mul_f32_e32 v7, 0x4f800000, v6
	s_nop 0
	v_cndmask_b32_e64 v6, v6, v7, s[14:15]
	v_sqrt_f32_e32 v7, v6
	s_nop 0
	v_add_u32_e32 v8, -1, v7
	v_fma_f32 v9, -v8, v7, v6
	v_cmp_ge_f32_e64 s[16:17], 0, v9
	v_add_u32_e32 v9, 1, v7
	s_nop 0
	v_cndmask_b32_e64 v8, v7, v8, s[16:17]
	v_fma_f32 v7, -v9, v7, v6
	v_cmp_lt_f32_e64 s[16:17], 0, v7
	s_nop 1
	v_cndmask_b32_e64 v7, v8, v9, s[16:17]
	v_mul_f32_e32 v8, 0x37800000, v7
	v_cndmask_b32_e64 v7, v7, v8, s[14:15]
	v_cmp_class_f32_e64 s[14:15], v6, v194
	v_add_f64 v[8:9], v[0:1], -v[14:15]
	s_nop 0
	v_cndmask_b32_e64 v6, v7, v6, s[14:15]
	v_add_f32_e32 v6, v6, v6
	v_fmamk_f32 v6, v6, 0x3db504f3, v195
	v_cvt_f64_f32_e32 v[6:7], v6
	v_cmp_lt_f64_e64 s[2:3], v[8:9], -v[6:7]
	s_and_b64 s[2:3], s[12:13], s[2:3]
	s_nop 0
	v_cndmask_b32_e64 v8, 0, 1, s[2:3]
	v_cmp_ne_u32_e64 s[12:13], 0, v8
	v_add_f64 v[8:9], v[0:1], -v[16:17]
	v_cmp_lt_f64_e64 s[2:3], v[8:9], -v[6:7]
	s_and_b64 s[2:3], s[10:11], s[2:3]
	s_bcnt1_i32_b64 s12, s[12:13]
	v_cndmask_b32_e64 v8, 0, 1, s[2:3]
	v_cmp_ne_u32_e64 s[10:11], 0, v8
	s_bcnt1_i32_b64 s2, s[10:11]
	s_add_i32 s10, s2, s12
	v_cmp_lt_f64_e64 s[2:3], v[4:5], -v[6:7]
	s_and_b64 s[2:3], s[8:9], s[2:3]
	s_nop 0
	v_cndmask_b32_e64 v4, 0, 1, s[2:3]
	v_cmp_ne_u32_e64 s[8:9], 0, v4
	s_bcnt1_i32_b64 s2, s[8:9]
	s_add_i32 s8, s10, s2
	v_cmp_lt_f64_e64 s[2:3], v[2:3], -v[6:7]
	s_and_b64 s[2:3], vcc, s[2:3]
	s_mov_b64 s[10:11], 0
	v_cndmask_b32_e64 v2, 0, 1, s[2:3]
	v_cmp_ne_u32_e32 vcc, 0, v2
	s_bcnt1_i32_b64 s2, vcc
	s_add_i32 s12, s8, s2
	s_ashr_i32 s8, s12, 31
	s_lshr_b32 s8, s8, 26
	s_add_i32 s8, s12, s8
	s_ashr_i32 s14, s8, 6
	s_cmp_lt_i32 s20, s14
	v_readfirstlane_b32 s3, v1
	v_readfirstlane_b32 s2, v0
	s_cselect_b64 s[8:9], -1, 0
	s_branch .LBB0_215

; __device__ __forceinline__ unsigned cvt_pk_bf16(float lo, float hi) { unsigned r; asm volatile("v_cvt_pk_bf16_f32 %0, %1, %2" : "=v"(r) : "v"(lo), "v"(hi)); return r; }
; __device__ __forceinline__ void ssm_pass1(ArgP a, LAS unsigned char* lds, int l, const int tid, const int item) {
;     ...
;             for (int i = 0; i < 8; ++i) { const f32x4 z4 = {0.f, 0.f, 0.f, 0.f};
;                 const f32x4 bu = __builtin_amdgcn_mfma_f32_16x16x32_bf16(ua, bbf[i], z4, 0, 0, 0);
; #pragma unroll
;                 for (int j = 0; j < 4; ++j) BU[(fq * 4 + j) * 130 + (i & 1) * 64 + (i >> 1) * 16 + fr] = bu[j]; }
; #pragma unroll 4
;             for (int tt = 0; tt < 16; ++tt) {
;                 const float br_ = BU[tt * 130 + lane], bi_ = BU[tt * 130 + 64 + lane];
;                 const float nxr = fmaf(ar, xr, fmaf(-ai, xi, br_)), nxi = fmaf(ar, xi, fmaf(ai, xr, bi_));
;                 xr = nxr; xi = nxi;
;                 const unsigned pk = cvt_pk_bf16(xr, xi);
;                 X[tt * 136 + lane] = (bf16_t)(pk & 0xffffu); X[tt * 136 + 64 + lane] = (bf16_t)(pk >> 16);
;             }
.LBB0_373:
	s_or_b64 exec, exec, s[0:1]
	v_mfma_f32_16x16x32_bf16 v[110:113], v[52:55], v[0:3], 0
	s_movk_i32 s0, 0x400
	s_nop 6
	ds_write_b32 v103, v110 offset:5376
	ds_write_b32 v104, v111 offset:5376
	ds_write_b32 v104, v112 offset:5896
	ds_write_b32 v104, v113 offset:6416
	v_mfma_f32_16x16x32_bf16 v[110:113], v[52:55], v[4:7], 0
	s_nop 7
	ds_write_b32 v103, v110 offset:5632
	ds_write_b32 v104, v111 offset:5632
	ds_write_b32 v104, v112 offset:6152
	ds_write_b32 v104, v113 offset:6672
	v_mfma_f32_16x16x32_bf16 v[110:113], v[52:55], v[8:11], 0
	s_nop 7
	ds_write_b32 v103, v110 offset:5440
	ds_write_b32 v104, v111 offset:5440
	ds_write_b32 v104, v112 offset:5960
	ds_write_b32 v104, v113 offset:6480
	v_mfma_f32_16x16x32_bf16 v[110:113], v[52:55], v[12:15], 0
	s_nop 7
	ds_write_b32 v103, v110 offset:5696
	ds_write_b32 v104, v111 offset:5696
	ds_write_b32 v104, v112 offset:6216
	ds_write_b32 v104, v113 offset:6736
	v_mfma_f32_16x16x32_bf16 v[110:113], v[52:55], v[16:19], 0
	s_nop 7
	ds_write_b32 v103, v110 offset:5504
	ds_write_b32 v104, v111 offset:5504
	ds_write_b32 v104, v112 offset:6024
	ds_write_b32 v104, v113 offset:6544
	v_mfma_f32_16x16x32_bf16 v[110:113], v[52:55], v[20:23], 0
	s_nop 7
	ds_write_b32 v103, v110 offset:5760
	ds_write_b32 v104, v111 offset:5760
	ds_write_b32 v104, v112 offset:6280
	ds_write_b32 v104, v113 offset:6800
	v_mfma_f32_16x16x32_bf16 v[110:113], v[52:55], v[24:27], 0
	s_nop 7
	ds_write_b32 v103, v110 offset:5568
	ds_write_b32 v104, v111 offset:5568
	ds_write_b32 v104, v112 offset:6088
	ds_write_b32 v104, v113 offset:6608
	v_mfma_f32_16x16x32_bf16 v[52:55], v[52:55], v[28:31], 0
	s_nop 7
	ds_write_b32 v103, v52 offset:5824
	ds_write_b32 v104, v53 offset:5824
	ds_write_b32 v104, v54 offset:6344
	ds_write_b32 v104, v55 offset:6864
	ds_read_b32 v114, v101 offset:256
	ds_read_b32 v115, v101 offset:0
	ds_read_b32 v116, v101 offset:776
	ds_read_b32 v117, v101 offset:520
	ds_read_b32 v118, v101 offset:1296
	ds_read_b32 v119, v101 offset:1040
	s_waitcnt lgkmcnt(4)
	v_pk_fma_f32 v[110:111], v[78:79], v[84:85], v[114:115]
	s_nop 0
	v_pk_fma_f32 v[54:55], v[80:81], v[84:85], v[110:111] op_sel:[0,0,1] op_sel_hi:[1,1,0]
	s_nop 0
	v_cvt_pk_bf16_f32 v53, v54, v55
	ds_write_b16 v73, v53 offset:1024
	ds_write_b16_d16_hi v73, v53 offset:1152
	ds_read_b32 v120, v101 offset:1816
	ds_read_b32 v121, v101 offset:1560
	s_waitcnt lgkmcnt(6)
	v_pk_fma_f32 v[110:111], v[78:79], v[54:55], v[116:117]
	s_nop 0
	v_pk_fma_f32 v[84:85], v[80:81], v[54:55], v[110:111] op_sel:[0,0,1] op_sel_hi:[1,1,0]
	s_nop 0
	v_cvt_pk_bf16_f32 v53, v84, v85
	ds_write_b16 v73, v53 offset:1296
	ds_write_b16_d16_hi v73, v53 offset:1424
	ds_read_b32 v114, v101 offset:2336
	ds_read_b32 v115, v101 offset:2080
	s_waitcnt lgkmcnt(8)
	v_pk_fma_f32 v[110:111], v[78:79], v[84:85], v[118:119]
	s_nop 0
	v_pk_fma_f32 v[54:55], v[80:81], v[84:85], v[110:111] op_sel:[0,0,1] op_sel_hi:[1,1,0]
	s_nop 0
	v_cvt_pk_bf16_f32 v53, v54, v55
	ds_write_b16 v73, v53 offset:1568
	ds_write_b16_d16_hi v73, v53 offset:1696
	ds_read_b32 v116, v101 offset:2856
	ds_read_b32 v117, v101 offset:2600
	s_waitcnt lgkmcnt(8)
	v_pk_fma_f32 v[110:111], v[78:79], v[54:55], v[120:121]
	s_nop 0
	v_pk_fma_f32 v[84:85], v[80:81], v[54:55], v[110:111] op_sel:[0,0,1] op_sel_hi:[1,1,0]
	s_nop 0
	v_cvt_pk_bf16_f32 v53, v84, v85
	ds_write_b16 v73, v53 offset:1840
	ds_write_b16_d16_hi v73, v53 offset:1968
	ds_read_b32 v118, v101 offset:3376
	ds_read_b32 v119, v101 offset:3120
	s_waitcnt lgkmcnt(8)
	v_pk_fma_f32 v[110:111], v[78:79], v[84:85], v[114:115]
	s_nop 0
	v_pk_fma_f32 v[54:55], v[80:81], v[84:85], v[110:111] op_sel:[0,0,1] op_sel_hi:[1,1,0]
	s_nop 0
	v_cvt_pk_bf16_f32 v53, v54, v55
	ds_write_b16 v73, v53 offset:2112
	ds_write_b16_d16_hi v73, v53 offset:2240
	ds_read_b32 v120, v101 offset:3896
	ds_read_b32 v121, v101 offset:3640
	s_waitcnt lgkmcnt(8)
	v_pk_fma_f32 v[110:111], v[78:79], v[54:55], v[116:117]
	s_nop 0
	v_pk_fma_f32 v[84:85], v[80:81], v[54:55], v[110:111] op_sel:[0,0,1] op_sel_hi:[1,1,0]
	s_nop 0
	v_cvt_pk_bf16_f32 v53, v84, v85
	ds_write_b16 v73, v53 offset:2384
	ds_write_b16_d16_hi v73, v53 offset:2512
	ds_read_b32 v114, v101 offset:4416
	ds_read_b32 v115, v101 offset:4160
	s_waitcnt lgkmcnt(8)
	v_pk_fma_f32 v[110:111], v[78:79], v[84:85], v[118:119]
	s_nop 0
	v_pk_fma_f32 v[54:55], v[80:81], v[84:85], v[110:111] op_sel:[0,0,1] op_sel_hi:[1,1,0]
	s_nop 0
	v_cvt_pk_bf16_f32 v53, v54, v55
	ds_write_b16 v73, v53 offset:2656
	ds_write_b16_d16_hi v73, v53 offset:2784
	ds_read_b32 v116, v101 offset:4936
	ds_read_b32 v117, v101 offset:4680
	s_waitcnt lgkmcnt(8)
	v_pk_fma_f32 v[110:111], v[78:79], v[54:55], v[120:121]
	s_nop 0
	v_pk_fma_f32 v[84:85], v[80:81], v[54:55], v[110:111] op_sel:[0,0,1] op_sel_hi:[1,1,0]
	s_nop 0
	v_cvt_pk_bf16_f32 v53, v84, v85
	ds_write_b16 v73, v53 offset:2928
	ds_write_b16_d16_hi v73, v53 offset:3056
	ds_read_b32 v118, v101 offset:5456
	ds_read_b32 v119, v101 offset:5200
	s_waitcnt lgkmcnt(8)
; #define LAS __attribute__((address_space(3)))
; __device__ __forceinline__ unsigned cvt_pk_bf16(float lo, float hi) { unsigned r; asm volatile("v_cvt_pk_bf16_f32 %0, %1, %2" : "=v"(r) : "v"(lo), "v"(hi)); return r; }
; __device__ __forceinline__ void ssm_pass1(ArgP a, LAS unsigned char* lds, int l, const int tid, const int item) {
;     ...
;             for (int tt = 0; tt < 16; ++tt) {
;                 const float br_ = BU[tt * 130 + lane], bi_ = BU[tt * 130 + 64 + lane];
;                 const float nxr = fmaf(ar, xr, fmaf(-ai, xi, br_)), nxi = fmaf(ar, xi, fmaf(ai, xr, bi_));
;                 xr = nxr; xi = nxi;
;                 const unsigned pk = cvt_pk_bf16(xr, xi);
;                 X[tt * 136 + lane] = (bf16_t)(pk & 0xffffu); X[tt * 136 + 64 + lane] = (bf16_t)(pk >> 16);
;             }
;             f32x4 acc = {0.f, 0.f, 0.f, 0.f};
; #pragma unroll
;             for (int ks = 0; ks < 4; ++ks) { const bf16x8 af = *(const LAS bf16x8*)(X + fr * 136 + ks * 32 + fq * 8); acc = __builtin_amdgcn_mfma_f32_16x16x32_bf16(af, cf[ks], acc, 0, 0, 0); }
; #pragma unroll
;             for (int j = 0; j < 4; ++j) { const int tok = fq * 4 + j; YL[(size_t)(tb + tok) * 512 + g * 16 + fr] = acc[j] + dsk * U[tok * 16 + fr]; }
;         }
;         float* e = E + (((size_t)chunk * 32 + g) * 64 + lane) * 2; e[0] = xr; e[1] = xi;
	v_pk_fma_f32 v[110:111], v[78:79], v[84:85], v[114:115]
	s_nop 0
	v_pk_fma_f32 v[54:55], v[80:81], v[84:85], v[110:111] op_sel:[0,0,1] op_sel_hi:[1,1,0]
	s_nop 0
	v_cvt_pk_bf16_f32 v53, v54, v55
	ds_write_b16 v73, v53 offset:3200
	ds_write_b16_d16_hi v73, v53 offset:3328
	ds_read_b32 v120, v101 offset:5976
	ds_read_b32 v121, v101 offset:5720
	s_waitcnt lgkmcnt(8)
	v_pk_fma_f32 v[110:111], v[78:79], v[54:55], v[116:117]
	s_nop 0
	v_pk_fma_f32 v[84:85], v[80:81], v[54:55], v[110:111] op_sel:[0,0,1] op_sel_hi:[1,1,0]
	s_nop 0
	v_cvt_pk_bf16_f32 v53, v84, v85
	ds_write_b16 v73, v53 offset:3472
	ds_write_b16_d16_hi v73, v53 offset:3600
	ds_read_b32 v114, v101 offset:6496
	ds_read_b32 v115, v101 offset:6240
	s_waitcnt lgkmcnt(8)
	v_pk_fma_f32 v[110:111], v[78:79], v[84:85], v[118:119]
	s_nop 0
	v_pk_fma_f32 v[54:55], v[80:81], v[84:85], v[110:111] op_sel:[0,0,1] op_sel_hi:[1,1,0]
	s_nop 0
	v_cvt_pk_bf16_f32 v53, v54, v55
	ds_write_b16 v73, v53 offset:3744
	ds_write_b16_d16_hi v73, v53 offset:3872
	ds_read_b32 v116, v101 offset:7016
	ds_read_b32 v117, v101 offset:6760
	s_waitcnt lgkmcnt(8)
	v_pk_fma_f32 v[110:111], v[78:79], v[54:55], v[120:121]
	s_nop 0
	v_pk_fma_f32 v[84:85], v[80:81], v[54:55], v[110:111] op_sel:[0,0,1] op_sel_hi:[1,1,0]
	s_nop 0
	v_cvt_pk_bf16_f32 v53, v84, v85
	ds_write_b16 v73, v53 offset:4016
	ds_write_b16_d16_hi v73, v53 offset:4144
	ds_read_b32 v118, v101 offset:7536
	ds_read_b32 v119, v101 offset:7280
	s_waitcnt lgkmcnt(8)
	v_pk_fma_f32 v[110:111], v[78:79], v[84:85], v[114:115]
	s_nop 0
	v_pk_fma_f32 v[54:55], v[80:81], v[84:85], v[110:111] op_sel:[0,0,1] op_sel_hi:[1,1,0]
	s_nop 0
	v_cvt_pk_bf16_f32 v53, v54, v55
	ds_write_b16 v73, v53 offset:4288
	ds_write_b16_d16_hi v73, v53 offset:4416
	ds_read_b32 v120, v101 offset:8056
	ds_read_b32 v121, v101 offset:7800
	s_waitcnt lgkmcnt(8)
	v_pk_fma_f32 v[110:111], v[78:79], v[54:55], v[116:117]
	s_nop 0
	v_pk_fma_f32 v[84:85], v[80:81], v[54:55], v[110:111] op_sel:[0,0,1] op_sel_hi:[1,1,0]
	s_nop 0
	v_cvt_pk_bf16_f32 v53, v84, v85
	ds_write_b16 v73, v53 offset:4560
	ds_write_b16_d16_hi v73, v53 offset:4688
	s_waitcnt lgkmcnt(6)
	v_pk_fma_f32 v[110:111], v[78:79], v[84:85], v[118:119]
	s_nop 0
	v_pk_fma_f32 v[54:55], v[80:81], v[84:85], v[110:111] op_sel:[0,0,1] op_sel_hi:[1,1,0]
	s_nop 0
	v_cvt_pk_bf16_f32 v53, v54, v55
	ds_write_b16 v73, v53 offset:4832
	ds_write_b16_d16_hi v73, v53 offset:4960
	s_waitcnt lgkmcnt(4)
	v_pk_fma_f32 v[110:111], v[78:79], v[54:55], v[120:121]
	s_nop 0
	v_pk_fma_f32 v[84:85], v[80:81], v[54:55], v[110:111] op_sel:[0,0,1] op_sel_hi:[1,1,0]
	s_nop 0
	v_cvt_pk_bf16_f32 v53, v84, v85
	ds_write_b16 v73, v53 offset:5104
	ds_write_b16_d16_hi v73, v53 offset:5232
	ds_read_b128 v[52:55], v105 offset:1024
	ds_read_b128 v[110:113], v105 offset:1088
	s_lshl_b32 s0, s14, 4
	s_add_i32 s0, s0, s3
	s_add_i32 s14, s14, 1
	s_cmp_eq_u32 s14, 16
	s_waitcnt lgkmcnt(1)
	v_mfma_f32_16x16x32_bf16 v[52:55], v[52:55], v[32:35], 0
	s_waitcnt lgkmcnt(0)
	v_mfma_f32_16x16x32_bf16 v[52:55], v[110:113], v[36:39], v[52:55]
	ds_read_b128 v[110:113], v105 offset:1152
	s_waitcnt lgkmcnt(0)
	v_mfma_f32_16x16x32_bf16 v[52:55], v[110:113], v[40:43], v[52:55]
	ds_read_b128 v[110:113], v105 offset:1216
	s_waitcnt lgkmcnt(0)
	v_mfma_f32_16x16x32_bf16 v[52:55], v[110:113], v[44:47], v[52:55]
	ds_read_b32 v110, v106
	s_waitcnt lgkmcnt(0)
	s_nop 5
	v_fma_f32 v52, v100, v110, v52
	v_or_b32_e32 v110, s0, v63
	v_ashrrev_i32_e32 v111, 31, v110
	v_lshlrev_b64 v[110:111], 11, v[110:111]
	v_lshl_add_u64 v[110:111], v[82:83], 0, v[110:111]
	global_store_dword v[110:111], v52, off
	ds_read_b32 v52, v107
	s_waitcnt lgkmcnt(0)
	v_fma_f32 v110, v100, v52, v53
	v_or_b32_e32 v52, s0, v90
	v_ashrrev_i32_e32 v53, 31, v52
	v_lshlrev_b64 v[52:53], 11, v[52:53]
	v_lshl_add_u64 v[52:53], v[82:83], 0, v[52:53]
	global_store_dword v[52:53], v110, off
	ds_read_b32 v52, v108
	s_waitcnt lgkmcnt(0)
	v_fma_f32 v54, v100, v52, v54
	v_or_b32_e32 v52, s0, v92
	v_ashrrev_i32_e32 v53, 31, v52
	v_lshlrev_b64 v[52:53], 11, v[52:53]
	v_lshl_add_u64 v[52:53], v[82:83], 0, v[52:53]
	global_store_dword v[52:53], v54, off
	ds_read_b32 v52, v109
	s_waitcnt lgkmcnt(0)
	v_fmac_f32_e32 v55, v100, v52
	v_or_b32_e32 v52, s0, v93
	v_ashrrev_i32_e32 v53, 31, v52
	v_lshlrev_b64 v[52:53], 11, v[52:53]
	v_lshl_add_u64 v[52:53], v[82:83], 0, v[52:53]
	global_store_dword v[52:53], v55, off
	s_cbranch_scc0 .LBB0_370
	s_ashr_i32 s3, s2, 31
	s_lshl_b64 s[0:1], s[2:3], 11
	s_add_u32 s0, s24, s0
	s_addc_u32 s1, s25, s1
	v_mov_b32_e32 v1, s1
	v_or_b32_e32 v0, s0, v186
	v_lshl_add_u64 v[0:1], v[0:1], 3, s[18:19]
	global_store_dwordx2 v[0:1], v[84:85], off
	s_branch .LBB0_302
